# v18 + half-step-2 partialSM inside PV MFMA gaps (exp results kept in v234-249 across the loop, copied at loop entry/exit); HS1 QK exps done in place
# baseline (speedup 1.0000x reference)
; #define SBAR() __builtin_amdgcn_sched_barrier(0)
; __device__ __forceinline__ int v_st(int k, int c) { const int kk = (k & ~0xC) | ((k & 4) << 1) | ((k & 8) >> 1); return ((kk >> 3) * 4 + (c >> 5)) * 512 + ((kk & 7) * 32 + (c & 31)) * 2; }
; __device__ __forceinline__ int v_rd_base(int lane) { return ((lane & 3) << 3) | (((lane >> 2) & 3) << 6) | (((lane >> 4) & 1) << 5) | (((lane >> 5) & 1) << 8); }
; #define VMW() asm volatile("s_waitcnt vmcnt(0)" ::: "memory")
; __device__ __forceinline__ void partialSM(f32x16& p0, f32x16& p1, float& m_reg, float& mn, float& alpha, bool rs) {
;     float pmax = p0[0]; for (int r = 1; r < 16; ++r) pmax = fmaxf(pmax, p0[r]); for (int r = 0; r < 16; ++r) pmax = fmaxf(pmax, p1[r]);
;     if (!rs) pmax = -__builtin_inff();
;     { auto rr = __builtin_amdgcn_permlane32_swap(__float_as_uint(pmax), __float_as_uint(pmax), false, false);
;       pmax = fmaxf(__uint_as_float(rr[0]), __uint_as_float(rr[1])); }
;     constexpr float C2 = 1.4426950408889634f * SCALE;
;     if (__builtin_expect(__all((pmax - m_reg) * SCALE <= THR), 1)) { mn = m_reg; alpha = 1.f; }
;     else { mn = fmaxf(m_reg, pmax); alpha = __builtin_amdgcn_exp2f((m_reg - mn) * C2); m_reg = mn; }
;     const float mnL = rs ? -mn * C2 : -__builtin_inff();
;     for (int r = 0; r < 16; ++r) p0[r] = fmaf(p0[r], C2, mnL); for (int r = 0; r < 16; ++r) p1[r] = fmaf(p1[r], C2, mnL);
;     for (int r = 0; r < 16; ++r) p0[r] = __builtin_amdgcn_exp2f(p0[r]);
; __device__ __forceinline__ void moba_block(const BlockRef& cur, const BlockRef& nxt, char* lds, Seam& S) {
;     ...
;     float m_reg = -1e30f, l_reg = 0; f32x16 o[4] = {};
;     const int sr = tid >> 4, sc = (tid & 15) * 8, vst0 = v_st(sr, sc), vst1 = v_st(32 + sr, sc), kws = KSWZ(sr, sc * 2);
;     const int vb0 = (int)(uintptr_t)V_lds + v_rd_base(lane);
;     const bf16* Kh = cur.K; const bf16* Vh = cur.V;
;     const int qb = cur.qb;
;     const unsigned sel = gate_select(S.qr, lds, qb, r32, hi);
;     ...
;     constexpr int NQL = 8;
;     ...
;     f32x16 pA0, pA1, pB0, pB1; float mnA, mnB, alA, alB; bf16x8 pa0, pa1, pa2, pa3;
;     SWRITE_HV(0); SBAR();
;     if (NT > 1) { SLOAD_H(Kh, Vh, KBASE(1)); }
;     SBAR(); qkt<0>(pA0, pA1, K_lds, r32, hi, S.qr);
;     MASKT(pA0, pA1, 0); partialSM(pA0, pA1, m_reg, mnA, alA, RSEL(0));
;     if (NT > 1) { VMW(); SWRITE_H(1); }
;     __syncthreads();
.LBB0_88:
	s_and_b32 s0, s3, 0x3fffffc0
	v_and_b32_e32 v51, 63, v183
	s_lshl_b32 s0, s0, 2
	s_lshl_b32 s2, s44, 2
	s_add_i32 s0, s0, 0
	v_lshlrev_b32_e32 v52, 8, v166
	v_and_b32_e32 v53, 0x70, v183
	v_lshlrev_b32_e32 v54, 4, v51
	s_xor_b64 s[10:11], s[10:11], -1
	s_add_i32 s2, s2, 4
	s_add_i32 s7, s0, 0x10000
	v_bitop3_b32 v53, v98, v52, v53 bitop3:0xde
	v_lshlrev_b32_e32 v52, 3, v51
	v_and_b32_e32 v54, 0xc0, v54
	v_lshlrev_b32_e32 v55, 1, v51
	v_and_or_b32 v54, v52, 24, v54
	v_and_b32_e32 v55, 32, v55
	v_and_b32_e32 v52, 0x100, v52
	s_cmp_lg_u32 0, -1
	v_or3_b32 v52, v54, v55, v52
	s_cselect_b32 s0, 0, 0
	v_add_u32_e32 v185, s0, v52
	v_and_b32_e32 v52, 1, v165
	v_cmp_eq_u32_e32 vcc, 1, v52
	v_max_f32_e32 v52, v19, v19
	v_max_f32_e32 v54, v18, v18
	v_max_f32_e32 v52, v54, v52
	v_max3_f32 v52, v52, v20, v21
	v_max3_f32 v52, v52, v22, v23
	v_max3_f32 v52, v52, v24, v25
	v_max3_f32 v52, v52, v26, v27
	v_max3_f32 v52, v52, v28, v29
	v_max3_f32 v52, v52, v30, v31
	v_max3_f32 v52, v52, v32, v33
	v_max3_f32 v52, v52, v2, v3
	v_max3_f32 v52, v52, v4, v5
	v_max3_f32 v52, v52, v6, v7
	v_max3_f32 v52, v52, v8, v9
	v_max3_f32 v52, v52, v10, v11
	s_cmp_lt_i32 s44, 1
	v_max3_f32 v52, v52, v12, v13
	s_cselect_b64 s[0:1], -1, 0
	v_max3_f32 v52, v52, v14, v15
	v_max3_f32 v52, v52, v16, v17
	s_or_b64 vcc, s[0:1], vcc
	v_cndmask_b32_e32 v52, v220, v52, vcc
	v_mov_b32_e32 v54, v52
	s_nop 1
	v_permlane32_swap_b32_e32 v52, v54
	v_max_f32_e32 v54, v54, v54
	v_max_f32_e32 v52, v52, v52
	v_max_f32_e32 v52, v52, v54
	v_add_f32_e32 v54, 0x7149f2ca, v52
	v_mul_f32_e32 v54, 0x3db504f3, v54
	v_max_f32_e32 v52, 0xf149f2ca, v52
	v_cmp_ge_f32_e64 s[38:39], s91, v54
	v_sub_f32_e32 v54, 0xf149f2ca, v52
	v_mul_f32_e32 v54, 0x3e0293ee, v54
	s_cmp_eq_u64 s[38:39], exec
	v_exp_f32_e32 v54, v54
	s_cselect_b64 s[38:39], -1, 0
	v_mov_b32_e32 v55, 0xf149f2ca
	v_cndmask_b32_e64 v198, v52, v55, s[38:39]
	v_mul_f32_e32 v52, 0xbe0293ee, v198
	v_cndmask_b32_e32 v52, v220, v52, vcc
	v_cndmask_b32_e64 v196, v54, 1.0, s[38:39]
	v_mov_b32_e32 v54, v52
	v_fmamk_f32 v18, v18, 0x3e0293ee, v52
	v_fmamk_f32 v19, v19, 0x3e0293ee, v52
	v_fmamk_f32 v20, v20, 0x3e0293ee, v52
	v_fmamk_f32 v21, v21, 0x3e0293ee, v52
	v_fmamk_f32 v22, v22, 0x3e0293ee, v52
	v_fmamk_f32 v23, v23, 0x3e0293ee, v52
	v_fmamk_f32 v24, v24, 0x3e0293ee, v52
	v_fmamk_f32 v25, v25, 0x3e0293ee, v52
	v_fmamk_f32 v26, v26, 0x3e0293ee, v52
	v_fmamk_f32 v27, v27, 0x3e0293ee, v52
	v_fmamk_f32 v28, v28, 0x3e0293ee, v52
	v_fmamk_f32 v29, v29, 0x3e0293ee, v52
	v_fmamk_f32 v30, v30, 0x3e0293ee, v52
	v_fmamk_f32 v31, v31, 0x3e0293ee, v52
	v_fmamk_f32 v32, v32, 0x3e0293ee, v52
	v_fmac_f32_e32 v54, 0x3e0293ee, v33
	s_add_i32 s0, s6, 0xbfffff45
	v_pk_fma_f32 v[178:179], v[2:3], s[20:21], v[52:53] op_sel_hi:[1,0,0]
	v_exp_f32_e32 v231, v18
	v_exp_f32_e32 v233, v19
	v_exp_f32_e32 v229, v20
	v_exp_f32_e32 v232, v21
	v_exp_f32_e32 v228, v22
	v_exp_f32_e32 v230, v23
	v_exp_f32_e32 v226, v24
	v_exp_f32_e32 v227, v25
	v_exp_f32_e32 v223, v26
	v_exp_f32_e32 v225, v27
	v_exp_f32_e32 v209, v28
	v_exp_f32_e32 v224, v29
	v_exp_f32_e32 v206, v30
	v_exp_f32_e32 v208, v31
	v_exp_f32_e32 v205, v32
	v_exp_f32_e32 v207, v54
	v_add_u32_e32 v2, s0, v184
	s_waitcnt vmcnt(0)
	v_add_u32_e32 v188, 0, v53
	v_cmp_gt_u32_e64 s[38:39], 32, v51
	v_lshl_add_u32 v186, v50, 2, s7
	v_sub_u32_e32 v197, v2, v50
	v_mov_b32_e32 v50, v99
	v_mov_b32_e32 v51, v99
	v_pk_fma_f32 v[154:155], v[16:17], s[20:21], v[52:53] op_sel_hi:[1,0,0]
	v_pk_fma_f32 v[160:161], v[14:15], s[20:21], v[52:53] op_sel_hi:[1,0,0]
	v_pk_fma_f32 v[180:181], v[12:13], s[20:21], v[52:53] op_sel_hi:[1,0,0]
	v_pk_fma_f32 v[152:153], v[10:11], s[20:21], v[52:53] op_sel_hi:[1,0,0]
	v_pk_fma_f32 v[156:157], v[8:9], s[20:21], v[52:53] op_sel_hi:[1,0,0]
	v_pk_fma_f32 v[158:159], v[6:7], s[20:21], v[52:53] op_sel_hi:[1,0,0]
	v_pk_fma_f32 v[162:163], v[4:5], s[20:21], v[52:53] op_sel_hi:[1,0,0]
	s_waitcnt vmcnt(3)
	ds_write_b128 v191, v[34:37] offset:16384
	s_waitcnt vmcnt(2)
	ds_write_b128 v192, v[38:41] offset:16384
	s_waitcnt vmcnt(1)
	ds_write_b128 v188, v[42:45] offset:49152
	s_waitcnt vmcnt(0)
	ds_write_b128 v188, v[46:49] offset:57344
	v_mov_b32_e32 v52, v99
	v_mov_b32_e32 v53, v99
	v_mov_b32_e32 v54, v99
	v_mov_b32_e32 v55, v99
	v_mov_b32_e32 v56, v99
	v_mov_b32_e32 v57, v99
	v_mov_b32_e32 v58, v99
	v_mov_b32_e32 v59, v99
	v_mov_b32_e32 v60, v99
	v_mov_b32_e32 v61, v99
	v_mov_b32_e32 v62, v99
	v_mov_b32_e32 v63, v99
	v_mov_b32_e32 v64, v99
	v_mov_b32_e32 v65, v99
	v_mov_b64_e32 v[34:35], v[50:51]
	v_mov_b64_e32 v[18:19], v[50:51]
	v_mov_b64_e32 v[2:3], v[50:51]
	s_mov_b32 s3, 3
	v_lshl_add_u64 v[170:171], s[22:23], 0, v[98:99]
	v_lshl_add_u64 v[176:177], s[30:31], 0, v[98:99]
	v_lshl_add_u32 v187, v184, 2, s7
	v_mov_b32_e32 v189, 0
	s_movk_i32 s7, 0x7f
	v_mov_b64_e32 v[36:37], v[52:53]
	v_mov_b64_e32 v[38:39], v[54:55]
	v_mov_b64_e32 v[40:41], v[56:57]
	v_mov_b64_e32 v[42:43], v[58:59]
	v_mov_b64_e32 v[44:45], v[60:61]
	v_mov_b64_e32 v[46:47], v[62:63]
	v_mov_b64_e32 v[48:49], v[64:65]
	v_mov_b64_e32 v[20:21], v[52:53]
	v_mov_b64_e32 v[22:23], v[54:55]
	v_mov_b64_e32 v[24:25], v[56:57]
	v_mov_b64_e32 v[26:27], v[58:59]
	v_mov_b64_e32 v[28:29], v[60:61]
	v_mov_b64_e32 v[30:31], v[62:63]
	v_mov_b64_e32 v[32:33], v[64:65]
	v_mov_b64_e32 v[4:5], v[52:53]
	v_mov_b64_e32 v[6:7], v[54:55]
	v_mov_b64_e32 v[8:9], v[56:57]
	v_mov_b64_e32 v[10:11], v[58:59]
	v_mov_b64_e32 v[12:13], v[60:61]
	v_mov_b64_e32 v[14:15], v[62:63]
	v_mov_b64_e32 v[16:17], v[64:65]
	v_mov_b32_e32 v234, v231
	v_mov_b32_e32 v235, v233
	v_mov_b32_e32 v236, v229
	v_mov_b32_e32 v237, v232
	v_mov_b32_e32 v238, v228
	v_mov_b32_e32 v239, v230
	v_mov_b32_e32 v240, v226
	v_mov_b32_e32 v241, v227
	v_mov_b32_e32 v242, v223
	v_mov_b32_e32 v243, v225
	v_mov_b32_e32 v244, v209
	v_mov_b32_e32 v245, v224
	v_mov_b32_e32 v246, v206
	v_mov_b32_e32 v247, v208
	v_mov_b32_e32 v248, v205
	v_mov_b32_e32 v249, v207
	s_waitcnt lgkmcnt(0)
	s_barrier
; __device__ __forceinline__ void finishSM(f32x16& p0, f32x16& p1, float alpha, float& l_reg, bf16x8& pa0, bf16x8& pa1, bf16x8& pa2, bf16x8& pa3) {
;     for (int r = 0; r < 16; ++r) p1[r] = __builtin_amdgcn_exp2f(p1[r]);
;     float ps = 0; for (int r = 0; r < 16; ++r) ps += p0[r]; for (int r = 0; r < 16; ++r) ps += p1[r];
;     { auto rr = __builtin_amdgcn_permlane32_swap(__float_as_uint(ps), __float_as_uint(ps), false, false);
;       ps = __uint_as_float(rr[0]) + __uint_as_float(rr[1]); }
;     l_reg = l_reg * alpha + ps;
;     ...
;     PK4(p0, 0, pa0); PK4(p0, 8, pa1); PK4(p1, 0, pa2); PK4(p1, 8, pa3);
;     ...
; }
; template <int KB>
; __device__ __forceinline__ void qkt(f32x16& p0, f32x16& p1, const char* K_lds, int r32, int hi, const bf16x8* qr) {
;     p0 = f32x16{}; p1 = f32x16{};
;     const char* kb[4];
; #pragma unroll
;     for (int dd = 0; dd < 4; ++dd) kb[dd] = K_lds + KB * SHM_K + KSWZ(r32, (dd * 16 + hi * 8) * 2);
; #pragma unroll
;     for (int d0 = 0; d0 < 8; ++d0) { const char* a = kb[d0 & 3] + (d0 >> 2) * 128;
;         bf16x8 b0 = *reinterpret_cast<const bf16x8*>(a);
;         bf16x8 b1 = *reinterpret_cast<const bf16x8*>(a + 32 * 256);
;         p0 = __builtin_amdgcn_mfma_f32_32x32x16_bf16(b0, qr[d0], p0, 0, 0, 0);
;         p1 = __builtin_amdgcn_mfma_f32_32x32x16_bf16(b1, qr[d0], p1, 0, 0, 0); }
; }
.LBB0_89:
	s_waitcnt vmcnt(0)
	ds_read_b128 v[66:69], v169 offset:49152
	ds_read_b128 v[70:73], v169 offset:57344
	ds_read_b128 v[100:103], v193 offset:49152
	ds_read_b128 v[136:139], v193 offset:57344
	s_waitcnt lgkmcnt(3)
	v_mfma_f32_32x32x16_bf16 v[82:97], v[66:69], v[132:135], 0
	v_add_f32_e32 v148, 0, v234
	v_add_f32_e32 v148, v235, v148
	v_add_f32_e32 v148, v236, v148
	v_add_f32_e32 v148, v237, v148
	v_add_f32_e32 v148, v238, v148
	s_waitcnt lgkmcnt(2)
	v_mfma_f32_32x32x16_bf16 v[66:81], v[70:73], v[132:135], 0
	v_add_f32_e32 v148, v239, v148
	v_add_f32_e32 v148, v240, v148
	v_add_f32_e32 v148, v241, v148
	v_add_f32_e32 v148, v242, v148
	v_add_f32_e32 v148, v243, v148
	s_waitcnt lgkmcnt(1)
	v_mfma_f32_32x32x16_bf16 v[82:97], v[100:103], v[128:131], v[82:97]
	v_add_f32_e32 v148, v244, v148
	v_add_f32_e32 v148, v245, v148
	v_add_f32_e32 v148, v246, v148
	v_add_f32_e32 v148, v247, v148
	v_add_f32_e32 v148, v248, v148
	s_waitcnt lgkmcnt(0)
	v_mfma_f32_32x32x16_bf16 v[66:81], v[136:139], v[128:131], v[66:81]
	v_add_f32_e32 v148, v249, v148
	v_exp_f32_e32 v140, v152
	v_exp_f32_e32 v141, v153
	v_exp_f32_e32 v142, v180
	v_exp_f32_e32 v143, v181
	ds_read_b128 v[100:103], v194 offset:49152
	ds_read_b128 v[136:139], v194 offset:57344
	s_waitcnt lgkmcnt(1)
	v_mfma_f32_32x32x16_bf16 v[82:97], v[100:103], v[124:127], v[82:97]
	v_exp_f32_e32 v144, v160
	v_exp_f32_e32 v145, v161
	v_exp_f32_e32 v146, v154
	v_exp_f32_e32 v147, v155
	v_exp_f32_e32 v178, v178
	s_waitcnt lgkmcnt(0)
	v_mfma_f32_32x32x16_bf16 v[66:81], v[136:139], v[124:127], v[66:81]
	v_exp_f32_e32 v179, v179
	v_exp_f32_e32 v162, v162
	v_exp_f32_e32 v163, v163
	v_add_f32_e32 v148, v178, v148
	v_add_f32_e32 v148, v179, v148
	ds_read_b128 v[100:103], v195 offset:49152
	ds_read_b128 v[136:139], v195 offset:57344
	s_waitcnt lgkmcnt(1)
	v_mfma_f32_32x32x16_bf16 v[82:97], v[100:103], v[120:123], v[82:97]
	v_add_f32_e32 v148, v162, v148
	v_exp_f32_e32 v158, v158
	v_exp_f32_e32 v159, v159
	v_exp_f32_e32 v156, v156
	v_exp_f32_e32 v157, v157
	s_waitcnt lgkmcnt(0)
	v_mfma_f32_32x32x16_bf16 v[66:81], v[136:139], v[120:123], v[66:81]
	v_add_f32_e32 v148, v163, v148
	v_add_f32_e32 v148, v158, v148
	v_add_f32_e32 v148, v159, v148
	v_add_f32_e32 v148, v156, v148
	v_add_f32_e32 v148, v157, v148
	ds_read_b128 v[100:103], v169 offset:49280
	ds_read_b128 v[136:139], v169 offset:57472
	s_waitcnt lgkmcnt(1)
	v_mfma_f32_32x32x16_bf16 v[82:97], v[100:103], v[116:119], v[82:97]
	v_add_f32_e32 v148, v140, v148
	v_add_f32_e32 v148, v141, v148
	v_add_f32_e32 v148, v142, v148
	v_add_f32_e32 v148, v143, v148
	v_add_f32_e32 v148, v144, v148
	s_waitcnt lgkmcnt(0)
	v_mfma_f32_32x32x16_bf16 v[66:81], v[136:139], v[116:119], v[66:81]
	v_add_f32_e32 v148, v145, v148
	v_add_f32_e32 v148, v146, v148
	v_add_f32_e32 v199, v147, v148
	v_mov_b32_e32 v200, v199
	s_nop 1
	v_permlane32_swap_b32_e32 v199, v200
	v_cvt_pk_bf16_f32 v148, v234, v235
	ds_read_b128 v[100:103], v193 offset:49280
	ds_read_b128 v[136:139], v193 offset:57472
	s_waitcnt lgkmcnt(1)
	v_mfma_f32_32x32x16_bf16 v[82:97], v[100:103], v[112:115], v[82:97]
	v_cvt_pk_bf16_f32 v149, v236, v237
	v_cvt_pk_bf16_f32 v150, v238, v239
	v_cvt_pk_bf16_f32 v151, v240, v241
	v_cvt_pk_bf16_f32 v152, v242, v243
	v_cvt_pk_bf16_f32 v153, v244, v245
	s_waitcnt lgkmcnt(0)
	v_mfma_f32_32x32x16_bf16 v[66:81], v[136:139], v[112:115], v[66:81]
	v_cvt_pk_bf16_f32 v154, v246, v247
	v_cvt_pk_bf16_f32 v155, v248, v249
	v_cvt_pk_bf16_f32 v158, v158, v159
	v_cvt_pk_bf16_f32 v159, v156, v157
	v_cvt_pk_bf16_f32 v156, v178, v179
	ds_read_b128 v[100:103], v194 offset:49280
	ds_read_b128 v[136:139], v194 offset:57472
	s_waitcnt lgkmcnt(1)
	v_mfma_f32_32x32x16_bf16 v[82:97], v[100:103], v[108:111], v[82:97]
	v_cvt_pk_bf16_f32 v157, v162, v163
	v_cvt_pk_bf16_f32 v160, v140, v141
	v_cvt_pk_bf16_f32 v161, v142, v143
	v_cvt_pk_bf16_f32 v162, v144, v145
	v_cvt_pk_bf16_f32 v163, v146, v147
	s_waitcnt lgkmcnt(0)
	v_mfma_f32_32x32x16_bf16 v[66:81], v[136:139], v[108:111], v[66:81]
	s_nop 0
	v_permlane32_swap_b32_e32 v148, v150
	v_permlane32_swap_b32_e32 v149, v151
	v_permlane32_swap_b32_e32 v152, v154
	v_permlane32_swap_b32_e32 v153, v155
	ds_read_b128 v[100:103], v195 offset:49280
	ds_read_b128 v[136:139], v195 offset:57472
	s_waitcnt lgkmcnt(1)
	v_mfma_f32_32x32x16_bf16 v[82:97], v[100:103], v[104:107], v[82:97]
	v_permlane32_swap_b32_e32 v156, v158
	v_permlane32_swap_b32_e32 v157, v159
	v_permlane32_swap_b32_e32 v160, v162
	v_permlane32_swap_b32_e32 v161, v163
	s_waitcnt lgkmcnt(0)
	v_mfma_f32_32x32x16_bf16 v[66:81], v[136:139], v[104:107], v[66:81]
	v_add_u32_e32 v178, s7, v166
	v_add_u32_e32 v100, 1, v178
	v_add_u32_e32 v102, 33, v178
	v_ashrrev_i32_e32 v101, 31, v100
	v_ashrrev_i32_e32 v103, 31, v102
	v_lshlrev_b64 v[140:141], 8, v[100:101]
	v_lshlrev_b64 v[142:143], 8, v[102:103]
	v_lshl_add_u64 v[100:101], v[170:171], 0, v[140:141]
	v_lshl_add_u64 v[136:137], v[170:171], 0, v[142:143]
	v_lshl_add_u64 v[140:141], v[176:177], 0, v[140:141]
	v_lshl_add_u64 v[144:145], v[176:177], 0, v[142:143]
	global_load_dwordx4 v[100:103], v[100:101], off
	s_nop 0
	global_load_dwordx4 v[136:139], v[136:137], off
	s_nop 0
	global_load_dwordx4 v[140:143], v[140:141], off
	s_nop 0
	global_load_dwordx4 v[144:147], v[144:145], off
	s_cmp_le_i32 s7, s6
	s_cbranch_scc0 .Lmy_hs1_slow
; __device__ __forceinline__ void partialSM(f32x16& p0, f32x16& p1, float& m_reg, float& mn, float& alpha, bool rs) {
;     float pmax = p0[0]; for (int r = 1; r < 16; ++r) pmax = fmaxf(pmax, p0[r]); for (int r = 0; r < 16; ++r) pmax = fmaxf(pmax, p1[r]);
;     if (!rs) pmax = -__builtin_inff();
;     { auto rr = __builtin_amdgcn_permlane32_swap(__float_as_uint(pmax), __float_as_uint(pmax), false, false);
;       pmax = fmaxf(__uint_as_float(rr[0]), __uint_as_float(rr[1])); }
;     constexpr float C2 = 1.4426950408889634f * SCALE;
;     if (__builtin_expect(__all((pmax - m_reg) * SCALE <= THR), 1)) { mn = m_reg; alpha = 1.f; }
;     else { mn = fmaxf(m_reg, pmax); alpha = __builtin_amdgcn_exp2f((m_reg - mn) * C2); m_reg = mn; }
;     const float mnL = rs ? -mn * C2 : -__builtin_inff();
;     for (int r = 0; r < 16; ++r) p0[r] = fmaf(p0[r], C2, mnL); for (int r = 0; r < 16; ++r) p1[r] = fmaf(p1[r], C2, mnL);
;     for (int r = 0; r < 16; ++r) p0[r] = __builtin_amdgcn_exp2f(p0[r]);
; template <int VB>
; __device__ __forceinline__ void pv_tile(f32x16* o, int vb0, bf16x8 pa0, bf16x8 pa1, bf16x8 pa2, bf16x8 pa3) {
;     ...
;     PV_D0(0); PV_D0(1); PV_D0(2); PV_D0(3);
	ds_read_b64_tr_b16 v[172:173], v185 offset:0
	ds_read_b64_tr_b16 v[174:175], v185 offset:0x800
	ds_read_b64_tr_b16 v[202:203], v185 offset:0x1000
	ds_read_b64_tr_b16 v[204:205], v185 offset:0x1800
	ds_read_b64_tr_b16 v[206:207], v185 offset:0x2000
	ds_read_b64_tr_b16 v[208:209], v185 offset:0x2800
	ds_read_b64_tr_b16 v[224:225], v185 offset:0x3000
	ds_read_b64_tr_b16 v[226:227], v185 offset:0x3800
	s_waitcnt lgkmcnt(0)
	s_nop 0
	v_mfma_f32_32x32x16_bf16 v[50:65], v[148:151], v[172:175], v[50:65]
	ds_read_b64_tr_b16 v[172:173], v185 offset:0x200
	ds_read_b64_tr_b16 v[174:175], v185 offset:0xa00
	v_mfma_f32_32x32x16_bf16 v[50:65], v[152:155], v[202:205], v[50:65]
	s_add_i32 s0, s3, -2
	s_lshr_b32 s8, s0, 2
	s_cmp_ge_i32 s8, s44
	s_cselect_b64 s[0:1], -1, 0
	s_lshl_b32 s8, 1, s8
	v_and_b32_e32 v250, s8, v165
	ds_read_b64_tr_b16 v[202:203], v185 offset:0x1200
	ds_read_b64_tr_b16 v[204:205], v185 offset:0x1a00
	v_mfma_f32_32x32x16_bf16 v[50:65], v[156:159], v[206:209], v[50:65]
	v_cmp_ne_u32_e32 vcc, 0, v250
	v_max_f32_e32 v250, v83, v83
	v_max_f32_e32 v251, v82, v82
	v_max_f32_e32 v250, v251, v250
	v_max3_f32 v250, v250, v84, v85
	ds_read_b64_tr_b16 v[206:207], v185 offset:0x2200
	ds_read_b64_tr_b16 v[208:209], v185 offset:0x2a00
	v_mfma_f32_32x32x16_bf16 v[50:65], v[160:163], v[224:227], v[50:65]
	v_max3_f32 v250, v250, v86, v87
	v_max3_f32 v250, v250, v88, v89
	v_max3_f32 v250, v250, v90, v91
	v_max3_f32 v250, v250, v92, v93
	v_max3_f32 v250, v250, v94, v95
	ds_read_b64_tr_b16 v[224:225], v185 offset:0x3200
	ds_read_b64_tr_b16 v[226:227], v185 offset:0x3a00
	s_waitcnt lgkmcnt(0)
	v_mfma_f32_32x32x16_bf16 v[34:49], v[148:151], v[172:175], v[34:49]
	v_max3_f32 v250, v250, v96, v97
	v_max3_f32 v250, v250, v66, v67
	v_max3_f32 v250, v250, v68, v69
	v_max3_f32 v250, v250, v70, v71
	v_max3_f32 v250, v250, v72, v73
	ds_read_b64_tr_b16 v[172:173], v185 offset:0x400
	ds_read_b64_tr_b16 v[174:175], v185 offset:0xc00
	v_mfma_f32_32x32x16_bf16 v[34:49], v[152:155], v[202:205], v[34:49]
	v_max3_f32 v250, v250, v74, v75
	v_max3_f32 v250, v250, v76, v77
	v_max3_f32 v250, v250, v78, v79
	s_or_b64 s[40:41], s[0:1], vcc
	v_max3_f32 v250, v250, v80, v81
	ds_read_b64_tr_b16 v[202:203], v185 offset:0x1400
	ds_read_b64_tr_b16 v[204:205], v185 offset:0x1c00
	v_mfma_f32_32x32x16_bf16 v[34:49], v[156:159], v[206:209], v[34:49]
	v_cndmask_b32_e64 v250, v220, v250, s[40:41]
	v_mov_b32_e32 v251, v250
	s_nop 1
	v_permlane32_swap_b32_e32 v250, v251
	v_max_f32_e32 v251, v251, v251
	v_max_f32_e32 v250, v250, v250
	v_max_f32_e32 v250, v250, v251
	ds_read_b64_tr_b16 v[206:207], v185 offset:0x2400
	ds_read_b64_tr_b16 v[208:209], v185 offset:0x2c00
	v_mfma_f32_32x32x16_bf16 v[34:49], v[160:163], v[224:227], v[34:49]
	v_sub_f32_e32 v251, v250, v198
	v_mul_f32_e32 v251, 0x3db504f3, v251
	v_cmp_ge_f32_e32 vcc, s91, v251
	v_max_f32_e32 v251, v198, v198
	v_max_f32_e32 v250, v251, v250
	ds_read_b64_tr_b16 v[224:225], v185 offset:0x3400
	ds_read_b64_tr_b16 v[226:227], v185 offset:0x3c00
	s_waitcnt lgkmcnt(0)
	v_mfma_f32_32x32x16_bf16 v[18:33], v[148:151], v[172:175], v[18:33]
	v_sub_f32_e32 v251, v198, v250
	v_mul_f32_e32 v251, 0x3e0293ee, v251
	v_exp_f32_e32 v251, v251
	s_cmp_eq_u64 vcc, exec
	s_cselect_b64 s[42:43], -1, 0
	v_cndmask_b32_e64 v179, v250, v198, s[42:43]
	ds_read_b64_tr_b16 v[172:173], v185 offset:0x600
	ds_read_b64_tr_b16 v[174:175], v185 offset:0xe00
	v_mfma_f32_32x32x16_bf16 v[18:33], v[152:155], v[202:205], v[18:33]
	v_mul_f32_e32 v222, 0xbe0293ee, v179
	v_cndmask_b32_e64 v180, v220, v222, s[40:41]
	v_fmamk_f32 v82, v82, 0x3e0293ee, v180
	v_fmamk_f32 v83, v83, 0x3e0293ee, v180
	v_fmamk_f32 v84, v84, 0x3e0293ee, v180
	ds_read_b64_tr_b16 v[202:203], v185 offset:0x1600
	ds_read_b64_tr_b16 v[204:205], v185 offset:0x1e00
	v_mfma_f32_32x32x16_bf16 v[18:33], v[156:159], v[206:209], v[18:33]
	v_fmamk_f32 v85, v85, 0x3e0293ee, v180
	v_fmamk_f32 v86, v86, 0x3e0293ee, v180
	v_fmamk_f32 v87, v87, 0x3e0293ee, v180
	v_fmamk_f32 v88, v88, 0x3e0293ee, v180
	v_fmamk_f32 v89, v89, 0x3e0293ee, v180
	ds_read_b64_tr_b16 v[206:207], v185 offset:0x2600
	ds_read_b64_tr_b16 v[208:209], v185 offset:0x2e00
	v_mfma_f32_32x32x16_bf16 v[18:33], v[160:163], v[224:227], v[18:33]
	v_fmamk_f32 v90, v90, 0x3e0293ee, v180
	v_fmamk_f32 v91, v91, 0x3e0293ee, v180
	v_fmamk_f32 v92, v92, 0x3e0293ee, v180
	v_fmamk_f32 v93, v93, 0x3e0293ee, v180
	v_fmamk_f32 v94, v94, 0x3e0293ee, v180
	ds_read_b64_tr_b16 v[224:225], v185 offset:0x3600
	ds_read_b64_tr_b16 v[226:227], v185 offset:0x3e00
	s_waitcnt lgkmcnt(0)
	v_mfma_f32_32x32x16_bf16 v[2:17], v[148:151], v[172:175], v[2:17]
	v_fmamk_f32 v95, v95, 0x3e0293ee, v180
	v_fmamk_f32 v96, v96, 0x3e0293ee, v180
	v_fmamk_f32 v97, v97, 0x3e0293ee, v180
	v_exp_f32_e32 v234, v82
	v_exp_f32_e32 v249, v83
	v_mfma_f32_32x32x16_bf16 v[2:17], v[152:155], v[202:205], v[2:17]
	v_exp_f32_e32 v235, v84
	v_exp_f32_e32 v248, v85
	v_exp_f32_e32 v236, v86
	v_exp_f32_e32 v247, v87
	v_exp_f32_e32 v237, v88
	v_mfma_f32_32x32x16_bf16 v[2:17], v[156:159], v[206:209], v[2:17]
	v_exp_f32_e32 v246, v89
	v_exp_f32_e32 v238, v90
	v_exp_f32_e32 v245, v91
	v_exp_f32_e32 v239, v92
	v_exp_f32_e32 v244, v93
	v_mfma_f32_32x32x16_bf16 v[2:17], v[160:163], v[224:227], v[2:17]
	v_exp_f32_e32 v240, v94
	v_exp_f32_e32 v243, v95
	v_exp_f32_e32 v241, v96
	v_exp_f32_e32 v242, v97
	v_mov_b32_e32 v149, v251
	s_mov_b32 s100, 1
	s_branch .Lmy_hs1_b1

; __device__ __forceinline__ void partialSM(f32x16& p0, f32x16& p1, float& m_reg, float& mn, float& alpha, bool rs) {
;     float pmax = p0[0]; for (int r = 1; r < 16; ++r) pmax = fmaxf(pmax, p0[r]); for (int r = 0; r < 16; ++r) pmax = fmaxf(pmax, p1[r]);
;     if (!rs) pmax = -__builtin_inff();
;     { auto rr = __builtin_amdgcn_permlane32_swap(__float_as_uint(pmax), __float_as_uint(pmax), false, false);
;       pmax = fmaxf(__uint_as_float(rr[0]), __uint_as_float(rr[1])); }
;     constexpr float C2 = 1.4426950408889634f * SCALE;
;     if (__builtin_expect(__all((pmax - m_reg) * SCALE <= THR), 1)) { mn = m_reg; alpha = 1.f; }
;     else { mn = fmaxf(m_reg, pmax); alpha = __builtin_amdgcn_exp2f((m_reg - mn) * C2); m_reg = mn; }
;     const float mnL = rs ? -mn * C2 : -__builtin_inff();
;     for (int r = 0; r < 16; ++r) p0[r] = fmaf(p0[r], C2, mnL); for (int r = 0; r < 16; ++r) p1[r] = fmaf(p1[r], C2, mnL);
;     for (int r = 0; r < 16; ++r) p0[r] = __builtin_amdgcn_exp2f(p0[r]);
; template <int VB>
; __device__ __forceinline__ void pv_tile(f32x16* o, int vb0, bf16x8 pa0, bf16x8 pa1, bf16x8 pa2, bf16x8 pa3) {
;     ...
;     PV_D0(0); PV_D0(1); PV_D0(2); PV_D0(3);
.LBB0_97:
	s_add_i32 s0, s7, 64
	s_cmp_le_i32 s0, s6
	s_cbranch_scc0 .Lmy_hs2_slow
	ds_read_b64_tr_b16 v[172:173], v185 offset:0x4000
	ds_read_b64_tr_b16 v[174:175], v185 offset:0x4800
	ds_read_b64_tr_b16 v[206:207], v185 offset:0x5000
	ds_read_b64_tr_b16 v[208:209], v185 offset:0x5800
	ds_read_b64_tr_b16 v[224:225], v185 offset:0x6000
	ds_read_b64_tr_b16 v[226:227], v185 offset:0x6800
	ds_read_b64_tr_b16 v[228:229], v185 offset:0x7000
	ds_read_b64_tr_b16 v[230:231], v185 offset:0x7800
	s_waitcnt lgkmcnt(0)
	s_nop 0
	v_mfma_f32_32x32x16_bf16 v[50:65], v[148:151], v[172:175], v[50:65]
	ds_read_b64_tr_b16 v[172:173], v185 offset:0x4200
	ds_read_b64_tr_b16 v[174:175], v185 offset:0x4a00
	v_mfma_f32_32x32x16_bf16 v[50:65], v[152:155], v[206:209], v[50:65]
	s_add_i32 s0, s3, -1
	s_lshr_b32 s8, s0, 2
	s_cmp_ge_i32 s8, s44
	s_cselect_b64 s[0:1], -1, 0
	s_lshl_b32 s8, 1, s8
	v_and_b32_e32 v250, s8, v165
	ds_read_b64_tr_b16 v[206:207], v185 offset:0x5200
	ds_read_b64_tr_b16 v[208:209], v185 offset:0x5a00
	v_mfma_f32_32x32x16_bf16 v[50:65], v[156:159], v[224:227], v[50:65]
	v_cmp_ne_u32_e32 vcc, 0, v250
	v_max_f32_e32 v250, v83, v83
	v_max_f32_e32 v251, v82, v82
	v_max_f32_e32 v250, v251, v250
	v_max3_f32 v250, v250, v84, v85
	ds_read_b64_tr_b16 v[224:225], v185 offset:0x6200
	ds_read_b64_tr_b16 v[226:227], v185 offset:0x6a00
	v_mfma_f32_32x32x16_bf16 v[50:65], v[160:163], v[228:231], v[50:65]
	v_max3_f32 v250, v250, v86, v87
	v_max3_f32 v250, v250, v88, v89
	v_max3_f32 v250, v250, v90, v91
	v_max3_f32 v250, v250, v92, v93
	v_max3_f32 v250, v250, v94, v95
	ds_read_b64_tr_b16 v[228:229], v185 offset:0x7200
	ds_read_b64_tr_b16 v[230:231], v185 offset:0x7a00
	s_waitcnt lgkmcnt(0)
	v_mfma_f32_32x32x16_bf16 v[34:49], v[148:151], v[172:175], v[34:49]
	v_max3_f32 v250, v250, v96, v97
	v_max3_f32 v250, v250, v66, v67
	v_max3_f32 v250, v250, v68, v69
	v_max3_f32 v250, v250, v70, v71
	v_max3_f32 v250, v250, v72, v73
	ds_read_b64_tr_b16 v[172:173], v185 offset:0x4400
	ds_read_b64_tr_b16 v[174:175], v185 offset:0x4c00
	v_mfma_f32_32x32x16_bf16 v[34:49], v[152:155], v[206:209], v[34:49]
	v_max3_f32 v250, v250, v74, v75
	v_max3_f32 v250, v250, v76, v77
	v_max3_f32 v250, v250, v78, v79
	v_max3_f32 v250, v250, v80, v81
	s_or_b64 s[40:41], s[0:1], vcc
	ds_read_b64_tr_b16 v[206:207], v185 offset:0x5400
	ds_read_b64_tr_b16 v[208:209], v185 offset:0x5c00
	v_mfma_f32_32x32x16_bf16 v[34:49], v[156:159], v[224:227], v[34:49]
	v_cndmask_b32_e64 v250, v220, v250, s[40:41]
	v_mov_b32_e32 v251, v250
	s_nop 1
	v_permlane32_swap_b32_e32 v250, v251
	v_max_f32_e32 v251, v251, v251
	v_max_f32_e32 v250, v250, v250
	v_max_f32_e32 v250, v250, v251
	ds_read_b64_tr_b16 v[224:225], v185 offset:0x6400
	ds_read_b64_tr_b16 v[226:227], v185 offset:0x6c00
	v_mfma_f32_32x32x16_bf16 v[34:49], v[160:163], v[228:231], v[34:49]
	v_sub_f32_e32 v251, v250, v179
	v_mul_f32_e32 v251, 0x3db504f3, v251
	v_cmp_ge_f32_e32 vcc, s91, v251
	v_max_f32_e32 v251, v179, v179
	v_max_f32_e32 v251, v251, v250
	ds_read_b64_tr_b16 v[228:229], v185 offset:0x7400
	ds_read_b64_tr_b16 v[230:231], v185 offset:0x7c00
	s_waitcnt lgkmcnt(0)
	v_mfma_f32_32x32x16_bf16 v[18:33], v[148:151], v[172:175], v[18:33]
	v_mov_b32_e32 v222, v251
	s_cmp_eq_u64 vcc, exec
	s_cselect_b64 s[42:43], -1, 0
	v_cndmask_b32_e64 v198, v222, v179, s[42:43]
	v_mul_f32_e32 v222, 0xbe0293ee, v198
	v_cndmask_b32_e64 v222, v220, v222, s[40:41]
	ds_read_b64_tr_b16 v[172:173], v185 offset:0x4600
	ds_read_b64_tr_b16 v[174:175], v185 offset:0x4e00
	v_mfma_f32_32x32x16_bf16 v[18:33], v[152:155], v[206:209], v[18:33]
	v_fmamk_f32 v82, v82, 0x3e0293ee, v222
	v_fmamk_f32 v83, v83, 0x3e0293ee, v222
	v_fmamk_f32 v84, v84, 0x3e0293ee, v222
	v_fmamk_f32 v85, v85, 0x3e0293ee, v222
	v_fmamk_f32 v86, v86, 0x3e0293ee, v222
	ds_read_b64_tr_b16 v[206:207], v185 offset:0x5600
	ds_read_b64_tr_b16 v[208:209], v185 offset:0x5e00
	v_mfma_f32_32x32x16_bf16 v[18:33], v[156:159], v[224:227], v[18:33]
	v_fmamk_f32 v87, v87, 0x3e0293ee, v222
	v_fmamk_f32 v88, v88, 0x3e0293ee, v222
	v_fmamk_f32 v89, v89, 0x3e0293ee, v222
	v_fmamk_f32 v90, v90, 0x3e0293ee, v222
	v_fmamk_f32 v91, v91, 0x3e0293ee, v222
	ds_read_b64_tr_b16 v[224:225], v185 offset:0x6600
	ds_read_b64_tr_b16 v[226:227], v185 offset:0x6e00
	v_mfma_f32_32x32x16_bf16 v[18:33], v[160:163], v[228:231], v[18:33]
	v_fmamk_f32 v92, v92, 0x3e0293ee, v222
	v_fmamk_f32 v93, v93, 0x3e0293ee, v222
	v_fmamk_f32 v94, v94, 0x3e0293ee, v222
	v_fmamk_f32 v95, v95, 0x3e0293ee, v222
	v_fmamk_f32 v96, v96, 0x3e0293ee, v222
	ds_read_b64_tr_b16 v[228:229], v185 offset:0x7600
	ds_read_b64_tr_b16 v[230:231], v185 offset:0x7e00
	s_waitcnt lgkmcnt(0)
	v_mfma_f32_32x32x16_bf16 v[2:17], v[148:151], v[172:175], v[2:17]
	v_fmamk_f32 v97, v97, 0x3e0293ee, v222
	v_exp_f32_e32 v234, v82
	v_exp_f32_e32 v235, v83
	v_exp_f32_e32 v236, v84
	v_exp_f32_e32 v237, v85
	v_mfma_f32_32x32x16_bf16 v[2:17], v[152:155], v[206:209], v[2:17]
	v_exp_f32_e32 v238, v86
	v_exp_f32_e32 v239, v87
	v_exp_f32_e32 v240, v88
	v_exp_f32_e32 v241, v89
	v_mfma_f32_32x32x16_bf16 v[2:17], v[156:159], v[224:227], v[2:17]
	v_exp_f32_e32 v242, v90
	v_exp_f32_e32 v243, v91
	v_exp_f32_e32 v244, v92
	v_exp_f32_e32 v245, v93
	v_mfma_f32_32x32x16_bf16 v[2:17], v[160:163], v[228:231], v[2:17]
	v_exp_f32_e32 v246, v94
	v_exp_f32_e32 v247, v95
	v_exp_f32_e32 v248, v96
	v_exp_f32_e32 v249, v97
	v_mov_b32_e32 v148, v250
	s_andn2_b64 vcc, exec, s[22:23]
	s_mov_b32 s100, 1
	s_branch .Lmy_hs2_b1
; __device__ __forceinline__ void mask_tile(f32x16& p0, f32x16& p1, int dq, unsigned W) {
;     const float NEG = -__builtin_inff();
; #pragma unroll
;     for (int r = 0; r < 16; ++r) {
;         const int c = (r & 3) + 8 * (r >> 2);
;         if ((unsigned)(dq - c) >= W) p0[r] = NEG;
;         if ((unsigned)(dq - c - 32) >= W) p1[r] = NEG;
;     }
; }
; template <int VB>
; __device__ __forceinline__ void pv_tile(f32x16* o, int vb0, bf16x8 pa0, bf16x8 pa1, bf16x8 pa2, bf16x8 pa3) {
;     ...
;     PV_D0(0); PV_D0(1); PV_D0(2); PV_D0(3);
.Lmy_hs2_slow:
	ds_read_b64_tr_b16 v[172:173], v185 offset:0x4000
	ds_read_b64_tr_b16 v[174:175], v185 offset:0x4800
	ds_read_b64_tr_b16 v[206:207], v185 offset:0x5000
	ds_read_b64_tr_b16 v[208:209], v185 offset:0x5800
	ds_read_b64_tr_b16 v[224:225], v185 offset:0x6000
	ds_read_b64_tr_b16 v[226:227], v185 offset:0x6800
	ds_read_b64_tr_b16 v[228:229], v185 offset:0x7000
	ds_read_b64_tr_b16 v[230:231], v185 offset:0x7800
	s_waitcnt lgkmcnt(0)
	s_nop 0
	v_mfma_f32_32x32x16_bf16 v[50:65], v[148:151], v[172:175], v[50:65]
	ds_read_b64_tr_b16 v[172:173], v185 offset:0x4200
	ds_read_b64_tr_b16 v[174:175], v185 offset:0x4a00
	v_mfma_f32_32x32x16_bf16 v[50:65], v[152:155], v[206:209], v[50:65]
	ds_read_b64_tr_b16 v[206:207], v185 offset:0x5200
	ds_read_b64_tr_b16 v[208:209], v185 offset:0x5a00
	v_mfma_f32_32x32x16_bf16 v[50:65], v[156:159], v[224:227], v[50:65]
	ds_read_b64_tr_b16 v[224:225], v185 offset:0x6200
	ds_read_b64_tr_b16 v[226:227], v185 offset:0x6a00
	v_mfma_f32_32x32x16_bf16 v[50:65], v[160:163], v[228:231], v[50:65]
	ds_read_b64_tr_b16 v[228:229], v185 offset:0x7200
	ds_read_b64_tr_b16 v[230:231], v185 offset:0x7a00
	s_waitcnt lgkmcnt(0)
	v_mfma_f32_32x32x16_bf16 v[34:49], v[148:151], v[172:175], v[34:49]
	ds_read_b64_tr_b16 v[172:173], v185 offset:0x4400
	ds_read_b64_tr_b16 v[174:175], v185 offset:0x4c00
	v_mfma_f32_32x32x16_bf16 v[34:49], v[152:155], v[206:209], v[34:49]
	ds_read_b64_tr_b16 v[206:207], v185 offset:0x5400
	ds_read_b64_tr_b16 v[208:209], v185 offset:0x5c00
	v_mfma_f32_32x32x16_bf16 v[34:49], v[156:159], v[224:227], v[34:49]
	ds_read_b64_tr_b16 v[224:225], v185 offset:0x6400
	ds_read_b64_tr_b16 v[226:227], v185 offset:0x6c00
	v_mfma_f32_32x32x16_bf16 v[34:49], v[160:163], v[228:231], v[34:49]
	ds_read_b64_tr_b16 v[228:229], v185 offset:0x7400
	ds_read_b64_tr_b16 v[230:231], v185 offset:0x7c00
	s_waitcnt lgkmcnt(0)
	v_mfma_f32_32x32x16_bf16 v[18:33], v[148:151], v[172:175], v[18:33]
	ds_read_b64_tr_b16 v[172:173], v185 offset:0x4600
	ds_read_b64_tr_b16 v[174:175], v185 offset:0x4e00
	v_mfma_f32_32x32x16_bf16 v[18:33], v[152:155], v[206:209], v[18:33]
	ds_read_b64_tr_b16 v[206:207], v185 offset:0x5600
	ds_read_b64_tr_b16 v[208:209], v185 offset:0x5e00
	v_mfma_f32_32x32x16_bf16 v[18:33], v[156:159], v[224:227], v[18:33]
	ds_read_b64_tr_b16 v[224:225], v185 offset:0x6600
	ds_read_b64_tr_b16 v[226:227], v185 offset:0x6e00
	v_mfma_f32_32x32x16_bf16 v[18:33], v[160:163], v[228:231], v[18:33]
	ds_read_b64_tr_b16 v[228:229], v185 offset:0x7600
	ds_read_b64_tr_b16 v[230:231], v185 offset:0x7e00
	s_waitcnt lgkmcnt(0)
	v_mfma_f32_32x32x16_bf16 v[2:17], v[148:151], v[172:175], v[2:17]
	s_add_i32 s0, s7, 64
	s_cmp_le_i32 s0, s6
	v_mfma_f32_32x32x16_bf16 v[2:17], v[152:155], v[206:209], v[2:17]
	v_mfma_f32_32x32x16_bf16 v[2:17], v[156:159], v[224:227], v[2:17]
	v_mfma_f32_32x32x16_bf16 v[2:17], v[160:163], v[228:231], v[2:17]
	v_add_u32_e32 v148, 0x4000003b, v197
	v_cmp_gt_u32_e32 vcc, 2.0, v148
	v_add_u32_e32 v148, 27, v197
	s_nop 0
	v_cndmask_b32_e32 v82, v220, v82, vcc
	v_cmp_lt_u32_e32 vcc, s33, v148
	v_add_u32_e32 v148, 58, v197
	s_nop 0
	v_cndmask_b32_e32 v66, v220, v66, vcc
	v_cmp_lt_u32_e32 vcc, s33, v148
	v_add_u32_e32 v148, 26, v197
	s_nop 0
	v_cndmask_b32_e32 v83, v220, v83, vcc
	v_cmp_lt_u32_e32 vcc, s33, v148
	v_add_u32_e32 v148, 57, v197
	s_nop 0
	v_cndmask_b32_e32 v67, v220, v67, vcc
	v_cmp_lt_u32_e32 vcc, s33, v148
	v_add_u32_e32 v148, 25, v197
	s_nop 0
	v_cndmask_b32_e32 v84, v220, v84, vcc
	v_cmp_lt_u32_e32 vcc, s33, v148
	v_add_u32_e32 v148, 56, v197
	s_nop 0
	v_cndmask_b32_e32 v68, v220, v68, vcc
	v_cmp_lt_u32_e32 vcc, s33, v148
	v_add_u32_e32 v148, 24, v197
	s_nop 0
	v_cndmask_b32_e32 v85, v220, v85, vcc
	v_cmp_lt_u32_e32 vcc, s33, v148
	v_add_u32_e32 v148, 51, v197
	s_nop 0
	v_cndmask_b32_e32 v69, v220, v69, vcc
	v_cmp_lt_u32_e32 vcc, s33, v148
	v_add_u32_e32 v148, 19, v197
	s_nop 0
	v_cndmask_b32_e32 v86, v220, v86, vcc
	v_cmp_lt_u32_e32 vcc, s33, v148
	v_add_u32_e32 v148, 50, v197
	s_nop 0
	v_cndmask_b32_e32 v70, v220, v70, vcc
	v_cmp_lt_u32_e32 vcc, s33, v148
	v_add_u32_e32 v148, 18, v197
	s_nop 0
	v_cndmask_b32_e32 v87, v220, v87, vcc
	v_cmp_lt_u32_e32 vcc, s33, v148
	v_add_u32_e32 v148, 49, v197
	s_nop 0
	v_cndmask_b32_e32 v71, v220, v71, vcc
	v_cmp_lt_u32_e32 vcc, s33, v148
	v_add_u32_e32 v148, 17, v197
	s_nop 0
	v_cndmask_b32_e32 v88, v220, v88, vcc
	v_cmp_lt_u32_e32 vcc, s33, v148
	v_add_u32_e32 v148, 48, v197
	s_nop 0
	v_cndmask_b32_e32 v72, v220, v72, vcc
	v_cmp_lt_u32_e32 vcc, s33, v148
	v_add_u32_e32 v148, 16, v197
	s_nop 0
	v_cndmask_b32_e32 v89, v220, v89, vcc
	v_cmp_lt_u32_e32 vcc, s33, v148
	v_add_u32_e32 v148, 43, v197
	s_nop 0
	v_cndmask_b32_e32 v73, v220, v73, vcc
	v_cmp_lt_u32_e32 vcc, s33, v148
	v_add_u32_e32 v148, 11, v197
	s_nop 0
	v_cndmask_b32_e32 v90, v220, v90, vcc
	v_cmp_lt_u32_e32 vcc, s33, v148
	v_add_u32_e32 v148, 42, v197
	s_nop 0
	v_cndmask_b32_e32 v74, v220, v74, vcc
	v_cmp_lt_u32_e32 vcc, s33, v148
	v_add_u32_e32 v148, 10, v197
	s_nop 0
	v_cndmask_b32_e32 v91, v220, v91, vcc
	v_cmp_lt_u32_e32 vcc, s33, v148
	v_add_u32_e32 v148, 41, v197
	s_nop 0
	v_cndmask_b32_e32 v75, v220, v75, vcc
	v_cmp_lt_u32_e32 vcc, s33, v148
	v_add_u32_e32 v148, 9, v197
	s_nop 0
	v_cndmask_b32_e32 v92, v220, v92, vcc
	v_cmp_lt_u32_e32 vcc, s33, v148
	v_add_u32_e32 v148, 40, v197
	s_nop 0
	v_cndmask_b32_e32 v76, v220, v76, vcc
	v_cmp_lt_u32_e32 vcc, s33, v148
	v_add_u32_e32 v148, 8, v197
	s_nop 0
	v_cndmask_b32_e32 v93, v220, v93, vcc
	v_cmp_lt_u32_e32 vcc, s33, v148
	v_add_u32_e32 v148, 35, v197
	s_nop 0
	v_cndmask_b32_e32 v77, v220, v77, vcc
	v_cmp_lt_u32_e32 vcc, s33, v148
	v_add_u32_e32 v148, 3, v197
	s_nop 0
	v_cndmask_b32_e32 v94, v220, v94, vcc
	v_cmp_lt_u32_e32 vcc, s33, v148
	v_add_u32_e32 v148, 34, v197
	s_nop 0
	v_cndmask_b32_e32 v78, v220, v78, vcc
	v_cmp_lt_u32_e32 vcc, s33, v148
	v_add_u32_e32 v148, 2, v197
	s_nop 0
	v_cndmask_b32_e32 v95, v220, v95, vcc
	v_cmp_lt_u32_e32 vcc, s33, v148
	v_add_u32_e32 v148, 33, v197
	s_nop 0
	v_cndmask_b32_e32 v79, v220, v79, vcc
	v_cmp_lt_u32_e32 vcc, s33, v148
	v_add_u32_e32 v148, 1, v197
	s_nop 0
	v_cndmask_b32_e32 v96, v220, v96, vcc
	v_cmp_lt_u32_e32 vcc, s33, v148
	v_add_u32_e32 v148, 32, v197
	s_nop 0
	v_cndmask_b32_e32 v80, v220, v80, vcc
	v_cmp_lt_u32_e32 vcc, s33, v148
	s_nop 1
	v_cndmask_b32_e32 v97, v220, v97, vcc
	v_cmp_lt_u32_e32 vcc, s33, v197
	s_nop 1
	v_cndmask_b32_e32 v81, v220, v81, vcc
; __device__ __forceinline__ void partialSM(f32x16& p0, f32x16& p1, float& m_reg, float& mn, float& alpha, bool rs) {
;     float pmax = p0[0]; for (int r = 1; r < 16; ++r) pmax = fmaxf(pmax, p0[r]); for (int r = 0; r < 16; ++r) pmax = fmaxf(pmax, p1[r]);
;     if (!rs) pmax = -__builtin_inff();
;     { auto rr = __builtin_amdgcn_permlane32_swap(__float_as_uint(pmax), __float_as_uint(pmax), false, false);
;       pmax = fmaxf(__uint_as_float(rr[0]), __uint_as_float(rr[1])); }
;     constexpr float C2 = 1.4426950408889634f * SCALE;
;     if (__builtin_expect(__all((pmax - m_reg) * SCALE <= THR), 1)) { mn = m_reg; alpha = 1.f; }
.LBB0_99:
	s_add_i32 s0, s3, -1
	s_lshr_b32 s8, s0, 2
	s_cmp_ge_i32 s8, s44
	s_cselect_b64 s[0:1], -1, 0
	s_lshl_b32 s8, 1, s8
	v_and_b32_e32 v148, s8, v165
	v_cmp_ne_u32_e32 vcc, 0, v148
	v_max_f32_e32 v148, v83, v83
	v_max_f32_e32 v149, v82, v82
	v_max_f32_e32 v148, v149, v148
	v_max3_f32 v148, v148, v84, v85
	v_max3_f32 v148, v148, v86, v87
	v_max3_f32 v148, v148, v88, v89
	v_max3_f32 v148, v148, v90, v91
	v_max3_f32 v148, v148, v92, v93
	v_max3_f32 v148, v148, v94, v95
	v_max3_f32 v148, v148, v96, v97
	v_max3_f32 v148, v148, v66, v67
	v_max3_f32 v148, v148, v68, v69
	v_max3_f32 v148, v148, v70, v71
	v_max3_f32 v148, v148, v72, v73
	v_max3_f32 v148, v148, v74, v75
	v_max3_f32 v148, v148, v76, v77
	v_max3_f32 v148, v148, v78, v79
	v_max3_f32 v148, v148, v80, v81
	s_or_b64 s[40:41], s[0:1], vcc
	v_cndmask_b32_e64 v148, v220, v148, s[40:41]
	v_mov_b32_e32 v149, v148
	s_nop 1
	v_permlane32_swap_b32_e32 v148, v149
	v_max_f32_e32 v149, v149, v149
	v_max_f32_e32 v148, v148, v148
	v_max_f32_e32 v148, v148, v149
	v_sub_f32_e32 v149, v148, v179
	v_mul_f32_e32 v149, 0x3db504f3, v149
	v_cmp_ge_f32_e32 vcc, s91, v149
	s_cmp_eq_u64 vcc, exec
	s_cselect_b64 s[42:43], -1, 0
	s_andn2_b64 vcc, exec, s[22:23]
	s_mov_b32 s100, 0
.Lmy_hs2_b1:
	s_barrier
	s_cbranch_vccnz .LBB0_101
	s_waitcnt vmcnt(0)
	s_waitcnt vmcnt(3)
	ds_write_b128 v191, v[100:103] offset:16384
	s_waitcnt vmcnt(2)
	ds_write_b128 v192, v[136:139] offset:16384
	s_waitcnt vmcnt(1)
	ds_write_b128 v188, v[140:143] offset:49152
	s_waitcnt vmcnt(0)
	ds_write_b128 v188, v[144:147] offset:57344

; #define SBAR() __builtin_amdgcn_sched_barrier(0)
; #define SLOAD_H(Kp, Vp, k0) do { S.st_v0 = load8(ROW(Vp, k0, sr)); S.st_v1 = load8(ROW(Vp, k0, 32 + sr));              \
;                          S.st_k0 = load8(ROW(Kp, k0, sr)); S.st_k1 = load8(ROW(Kp, k0, 32 + sr)); } while (0)
; __device__ __forceinline__ void partialSM(f32x16& p0, f32x16& p1, float& m_reg, float& mn, float& alpha, bool rs) {
;     ...
;     else { mn = fmaxf(m_reg, pmax); alpha = __builtin_amdgcn_exp2f((m_reg - mn) * C2); m_reg = mn; }
;     const float mnL = rs ? -mn * C2 : -__builtin_inff();
;     for (int r = 0; r < 16; ++r) p0[r] = fmaf(p0[r], C2, mnL); for (int r = 0; r < 16; ++r) p1[r] = fmaf(p1[r], C2, mnL);
;     for (int r = 0; r < 16; ++r) p0[r] = __builtin_amdgcn_exp2f(p0[r]);
; }
; __device__ __forceinline__ void finishSM(f32x16& p0, f32x16& p1, float alpha, float& l_reg, bf16x8& pa0, bf16x8& pa1, bf16x8& pa2, bf16x8& pa3) {
;     for (int r = 0; r < 16; ++r) p1[r] = __builtin_amdgcn_exp2f(p1[r]);
;     float ps = 0; for (int r = 0; r < 16; ++r) ps += p0[r]; for (int r = 0; r < 16; ++r) ps += p1[r];
;     { auto rr = __builtin_amdgcn_permlane32_swap(__float_as_uint(ps), __float_as_uint(ps), false, false);
;       ps = __uint_as_float(rr[0]) + __uint_as_float(rr[1]); }
;     l_reg = l_reg * alpha + ps;
; __device__ __forceinline__ void moba_block(const BlockRef& cur, const BlockRef& nxt, char* lds, Seam& S) {
;     ...
;     const bool even = (NT & 1) == 0;
;     if (even) { SBAR(); qkt<1>(pB0, pB1, K_lds, r32, hi, S.qr); SBAR(); }
;     SLOAD_H(nxt.K, nxt.V, 0); SBAR();
; #pragma unroll
;     for (int d0 = 0; d0 < 8; ++d0) S.qr[d0] = load8(nxt.Q + (size_t)(wid * QBLK + r32) * D + d0 * 16 + hi * 8);
.LBB0_105:
	s_cmp_eq_u32 s100, 1
	s_cbranch_scc1 .Lmy_hs2_ft
	v_cndmask_b32_e64 v198, v100, v179, s[42:43]
	v_mul_f32_e32 v100, 0xbe0293ee, v198
	v_cndmask_b32_e64 v100, v220, v100, s[40:41]
	v_mov_b32_e32 v101, v100
	v_fmamk_f32 v82, v82, 0x3e0293ee, v100
	v_fmamk_f32 v83, v83, 0x3e0293ee, v100
	v_fmamk_f32 v84, v84, 0x3e0293ee, v100
	v_fmamk_f32 v85, v85, 0x3e0293ee, v100
	v_fmamk_f32 v86, v86, 0x3e0293ee, v100
	v_fmamk_f32 v87, v87, 0x3e0293ee, v100
	v_fmamk_f32 v88, v88, 0x3e0293ee, v100
	v_fmamk_f32 v89, v89, 0x3e0293ee, v100
	v_fmamk_f32 v90, v90, 0x3e0293ee, v100
	v_fmamk_f32 v91, v91, 0x3e0293ee, v100
	v_fmamk_f32 v92, v92, 0x3e0293ee, v100
	v_fmamk_f32 v93, v93, 0x3e0293ee, v100
	v_fmamk_f32 v94, v94, 0x3e0293ee, v100
	v_fmamk_f32 v95, v95, 0x3e0293ee, v100
	v_fmamk_f32 v96, v96, 0x3e0293ee, v100
	v_fmac_f32_e32 v101, 0x3e0293ee, v97
	v_exp_f32_e32 v234, v82
	v_exp_f32_e32 v235, v83
	v_exp_f32_e32 v236, v84
	v_exp_f32_e32 v237, v85
	v_exp_f32_e32 v238, v86
	v_exp_f32_e32 v239, v87
	v_exp_f32_e32 v240, v88
	v_exp_f32_e32 v241, v89
	v_exp_f32_e32 v242, v90
	v_exp_f32_e32 v243, v91
	v_exp_f32_e32 v244, v92
	v_exp_f32_e32 v245, v93
	v_exp_f32_e32 v246, v94
	v_exp_f32_e32 v247, v95
	v_exp_f32_e32 v248, v96
	v_exp_f32_e32 v249, v101
	s_branch .Lmy_hs2_p1
.Lmy_hs2_ft:
	v_mov_b32_e32 v100, v222
.Lmy_hs2_p1:
	v_pk_fma_f32 v[178:179], v[66:67], s[20:21], v[100:101] op_sel_hi:[1,0,0]
	v_add_f32_e32 v66, v199, v200
	v_fmac_f32_e32 v66, v196, v189
	v_add_f32_e32 v189, v203, v204
	s_add_i32 s0, s3, 2
	s_add_i32 s1, s3, 1
	s_addk_i32 s7, 0x80
	v_pk_fma_f32 v[162:163], v[68:69], s[20:21], v[100:101] op_sel_hi:[1,0,0]
	v_pk_fma_f32 v[158:159], v[70:71], s[20:21], v[100:101] op_sel_hi:[1,0,0]
	v_pk_fma_f32 v[156:157], v[72:73], s[20:21], v[100:101] op_sel_hi:[1,0,0]
	v_pk_fma_f32 v[152:153], v[74:75], s[20:21], v[100:101] op_sel_hi:[1,0,0]
	v_pk_fma_f32 v[180:181], v[76:77], s[20:21], v[100:101] op_sel_hi:[1,0,0]
	v_pk_fma_f32 v[160:161], v[78:79], s[20:21], v[100:101] op_sel_hi:[1,0,0]
	v_pk_fma_f32 v[154:155], v[80:81], s[20:21], v[100:101] op_sel_hi:[1,0,0]
	v_fmac_f32_e32 v189, v66, v202
	s_cmp_lt_u32 s1, s2
	v_add_u32_e32 v197, 0xffffff80, v197
	s_waitcnt lgkmcnt(0)
	s_barrier
	s_cbranch_scc0 .LBB0_107
	s_mov_b32 s3, s0
	v_mov_b32_e32 v196, v201
	s_branch .LBB0_89
.LBB0_107:
	v_mov_b32_e32 v231, v234
	v_mov_b32_e32 v233, v235
	v_mov_b32_e32 v229, v236
	v_mov_b32_e32 v232, v237
	v_mov_b32_e32 v228, v238
	v_mov_b32_e32 v230, v239
	v_mov_b32_e32 v226, v240
	v_mov_b32_e32 v227, v241
	v_mov_b32_e32 v223, v242
	v_mov_b32_e32 v225, v243
	v_mov_b32_e32 v209, v244
	v_mov_b32_e32 v224, v245
	v_mov_b32_e32 v206, v246
	v_mov_b32_e32 v208, v247
	v_mov_b32_e32 v205, v248
	v_mov_b32_e32 v207, v249
	ds_read_b128 v[66:69], v169 offset:49152
	ds_read_b128 v[82:85], v169 offset:49280
	ds_read_b128 v[86:89], v193 offset:49152
	ds_read_b128 v[90:93], v193 offset:49280
	s_waitcnt lgkmcnt(3)
	v_mfma_f32_32x32x16_bf16 v[66:81], v[66:69], v[132:135], 0
	s_waitcnt lgkmcnt(1)
	v_mfma_f32_32x32x16_bf16 v[66:81], v[86:89], v[128:131], v[66:81]
	ds_read_b128 v[86:89], v194 offset:49152
	ds_read_b128 v[94:97], v194 offset:49280
	s_waitcnt lgkmcnt(1)
	v_mfma_f32_32x32x16_bf16 v[66:81], v[86:89], v[124:127], v[66:81]
	ds_read_b128 v[86:89], v195 offset:49152
	ds_read_b128 v[100:103], v195 offset:49280
	s_waitcnt lgkmcnt(1)
	v_mfma_f32_32x32x16_bf16 v[66:81], v[86:89], v[120:123], v[66:81]
	v_mfma_f32_32x32x16_bf16 v[66:81], v[82:85], v[116:119], v[66:81]
	ds_read_b128 v[82:85], v169 offset:57344
	s_waitcnt vmcnt(1)
	ds_read_b128 v[140:143], v169 offset:57472
	ds_read_b128 v[170:173], v193 offset:57344
	ds_read_b128 v[174:177], v193 offset:57472
	ds_read_b128 v[234:237], v194 offset:57344
	ds_read_b128 v[238:241], v194 offset:57472
	ds_read_b128 v[242:245], v195 offset:57344
	ds_read_b128 v[192:195], v195 offset:57472
	v_mfma_f32_32x32x16_bf16 v[66:81], v[90:93], v[112:115], v[66:81]
	v_mfma_f32_32x32x16_bf16 v[66:81], v[94:97], v[108:111], v[66:81]
	s_waitcnt lgkmcnt(8)
	v_mfma_f32_32x32x16_bf16 v[66:81], v[100:103], v[104:107], v[66:81]
	v_lshlrev_b64 v[86:87], 8, v[166:167]
	v_ashrrev_i32_e32 v169, 31, v168
	v_lshl_add_u64 v[88:89], s[16:17], 0, v[86:87]
	v_lshlrev_b64 v[90:91], 8, v[168:169]
	v_lshl_add_u64 v[88:89], v[88:89], 0, v[98:99]
	v_lshl_add_u64 v[92:93], s[16:17], 0, v[90:91]
	v_lshl_add_u64 v[86:87], s[28:29], 0, v[86:87]
	v_lshl_add_u64 v[92:93], v[92:93], 0, v[98:99]
	global_load_dwordx4 v[100:103], v[88:89], off
	global_load_dwordx4 v[136:139], v[92:93], off
	v_lshl_add_u64 v[86:87], v[86:87], 0, v[98:99]
	v_lshl_add_u64 v[88:89], s[28:29], 0, v[90:91]
	v_lshl_add_u64 v[88:89], v[88:89], 0, v[98:99]
	global_load_dwordx4 v[144:147], v[86:87], off
	global_load_dwordx4 v[148:151], v[88:89], off
	s_waitcnt lgkmcnt(7)
	v_mfma_f32_32x32x16_bf16 v[82:97], v[82:85], v[132:135], 0
	v_mov_b32_e32 v165, v99
	s_waitcnt lgkmcnt(5)
	v_mfma_f32_32x32x16_bf16 v[82:97], v[170:173], v[128:131], v[82:97]
	s_waitcnt lgkmcnt(3)
	v_mfma_f32_32x32x16_bf16 v[82:97], v[234:237], v[124:127], v[82:97]
	s_waitcnt lgkmcnt(1)
	v_mfma_f32_32x32x16_bf16 v[82:97], v[242:245], v[120:123], v[82:97]
	v_mfma_f32_32x32x16_bf16 v[82:97], v[140:143], v[116:119], v[82:97]
	v_or_b32_e32 v116, s94, v184
	v_ashrrev_i32_e32 v117, 31, v116
	v_lshlrev_b64 v[116:117], 8, v[116:117]
	v_lshl_add_u64 v[116:117], s[14:15], 0, v[116:117]
	v_lshl_add_u64 v[140:141], v[116:117], 0, v[164:165]
	v_mfma_f32_32x32x16_bf16 v[82:97], v[174:177], v[112:115], v[82:97]
	global_load_dwordx4 v[132:135], v[140:141], off
	global_load_dwordx4 v[128:131], v[140:141], off offset:32
	global_load_dwordx4 v[124:127], v[140:141], off offset:64
	global_load_dwordx4 v[120:123], v[140:141], off offset:96
	global_load_dwordx4 v[116:119], v[140:141], off offset:128
	global_load_dwordx4 v[112:115], v[140:141], off offset:160
	v_mfma_f32_32x32x16_bf16 v[82:97], v[238:241], v[108:111], v[82:97]
	global_load_dwordx4 v[108:111], v[140:141], off offset:192
	s_nop 0
	global_load_dwordx4 v[140:143], v[140:141], off offset:224
	s_waitcnt lgkmcnt(0)
; #define SBAR() __builtin_amdgcn_sched_barrier(0)
; #define RESC(a) do { if (__any((a) < 1.f)) { if (hi == 0) al_l[r32] = (a); asm volatile("s_waitcnt lgkmcnt(0)" ::: "memory");              \
;                      for (int d_ = 0; d_ < 4; ++d_) for (int r = 0; r < 16; ++r) o[d_][r] *= al_l[crow(r, hi)]; } } while (0)
; #define MASKT(P0_, P1_, t) do { const int kb_ = KBASE(t); if (kb_ + KVBLK - 1 > qlo) mask_tile(P0_, P1_, qm - kb_, (unsigned)W); } while (0)
; __device__ __forceinline__ void finishSM(f32x16& p0, f32x16& p1, float alpha, float& l_reg, bf16x8& pa0, bf16x8& pa1, bf16x8& pa2, bf16x8& pa3) {
;     for (int r = 0; r < 16; ++r) p1[r] = __builtin_amdgcn_exp2f(p1[r]);
;     float ps = 0; for (int r = 0; r < 16; ++r) ps += p0[r]; for (int r = 0; r < 16; ++r) ps += p1[r];
;     { auto rr = __builtin_amdgcn_permlane32_swap(__float_as_uint(ps), __float_as_uint(ps), false, false);
;       ps = __uint_as_float(rr[0]) + __uint_as_float(rr[1]); }
;     l_reg = l_reg * alpha + ps;
;     ...
;     PK4(p0, 0, pa0); PK4(p0, 8, pa1); PK4(p1, 0, pa2); PK4(p1, 8, pa3);
;     ...
; }
; __device__ __forceinline__ void moba_block(const BlockRef& cur, const BlockRef& nxt, char* lds, Seam& S) {
;     ...
;     finishSM(pA0, pA1, alA, l_reg, pa0, pa1, pa2, pa3); SBAR();
;     pv_tile<0>(o, vb0, pa0, pa1, pa2, pa3);
;     if (even) { MASKT(pB0, pB1, NT - 1); partialSM(pB0, pB1, m_reg, mnB, alB, RSEL(NT - 1)); __syncthreads(); RESC(alB);
	v_mfma_f32_32x32x16_bf16 v[82:97], v[192:195], v[104:107], v[82:97]
	v_add_f32_e32 v98, 0, v231
	v_add_f32_e32 v98, v233, v98
	v_add_f32_e32 v98, v229, v98
	v_add_f32_e32 v98, v232, v98
	v_add_f32_e32 v98, v228, v98
	v_add_f32_e32 v98, v230, v98
	v_add_f32_e32 v98, v226, v98
	v_add_f32_e32 v98, v227, v98
	v_add_f32_e32 v98, v223, v98
	v_add_f32_e32 v98, v225, v98
	v_add_f32_e32 v98, v209, v98
	v_add_f32_e32 v98, v224, v98
	v_exp_f32_e32 v105, v178
	v_add_f32_e32 v98, v206, v98
	v_exp_f32_e32 v106, v179
	v_add_f32_e32 v98, v208, v98
	v_exp_f32_e32 v107, v162
	v_add_f32_e32 v98, v205, v98
	v_exp_f32_e32 v162, v163
	v_add_f32_e32 v98, v207, v98
	v_exp_f32_e32 v163, v158
	v_add_f32_e32 v98, v105, v98
	v_exp_f32_e32 v164, v159
	v_add_f32_e32 v98, v106, v98
	v_exp_f32_e32 v165, v156
	v_add_f32_e32 v98, v107, v98
	v_exp_f32_e32 v166, v157
	v_add_f32_e32 v98, v162, v98
	v_exp_f32_e32 v167, v152
	v_add_f32_e32 v98, v163, v98
	v_exp_f32_e32 v168, v153
	v_add_f32_e32 v98, v164, v98
	v_exp_f32_e32 v169, v180
	v_add_f32_e32 v98, v165, v98
	v_exp_f32_e32 v170, v181
	v_add_f32_e32 v98, v166, v98
	v_exp_f32_e32 v171, v160
	v_add_f32_e32 v98, v167, v98
	v_exp_f32_e32 v172, v161
	v_add_f32_e32 v98, v168, v98
	v_exp_f32_e32 v173, v154
	v_add_f32_e32 v98, v169, v98
	v_exp_f32_e32 v174, v155
	v_add_f32_e32 v98, v170, v98
	v_add_f32_e32 v98, v171, v98
	v_add_f32_e32 v98, v172, v98
	v_add_f32_e32 v98, v173, v98
	v_add_f32_e32 v98, v174, v98
	v_mov_b32_e32 v104, v98
	s_nop 1
	v_permlane32_swap_b32_e32 v98, v104
	v_cvt_pk_bf16_f32 v152, v231, v233
	v_cvt_pk_bf16_f32 v153, v229, v232
	v_cvt_pk_bf16_f32 v154, v228, v230
	v_cvt_pk_bf16_f32 v155, v226, v227
	v_cvt_pk_bf16_f32 v156, v223, v225
	v_cvt_pk_bf16_f32 v157, v209, v224
	v_cvt_pk_bf16_f32 v158, v206, v208
	v_cvt_pk_bf16_f32 v159, v205, v207
	v_cvt_pk_bf16_f32 v160, v105, v106
	v_cvt_pk_bf16_f32 v161, v107, v162
	v_cvt_pk_bf16_f32 v162, v163, v164
	v_cvt_pk_bf16_f32 v163, v165, v166
	v_cvt_pk_bf16_f32 v164, v167, v168
	v_cvt_pk_bf16_f32 v165, v169, v170
	v_cvt_pk_bf16_f32 v166, v171, v172
	v_cvt_pk_bf16_f32 v167, v173, v174
	s_nop 0
	v_permlane32_swap_b32_e32 v152, v154
	v_permlane32_swap_b32_e32 v153, v155
	v_permlane32_swap_b32_e32 v156, v158
	v_permlane32_swap_b32_e32 v157, v159
	v_permlane32_swap_b32_e32 v160, v162
	v_permlane32_swap_b32_e32 v161, v163
	v_permlane32_swap_b32_e32 v164, v166
	v_permlane32_swap_b32_e32 v165, v167
	ds_read_b64_tr_b16 v[168:169], v185 offset:0
	ds_read_b64_tr_b16 v[170:171], v185 offset:0x800
	ds_read_b64_tr_b16 v[172:173], v185 offset:0x1000
	ds_read_b64_tr_b16 v[174:175], v185 offset:0x1800
	ds_read_b64_tr_b16 v[176:177], v185 offset:0x2000
	ds_read_b64_tr_b16 v[178:179], v185 offset:0x2800
	ds_read_b64_tr_b16 v[192:193], v185 offset:0x3000
	ds_read_b64_tr_b16 v[194:195], v185 offset:0x3800
	s_waitcnt lgkmcnt(0)
	s_nop 0
	v_mfma_f32_32x32x16_bf16 v[50:65], v[152:155], v[168:171], v[50:65]
	ds_read_b64_tr_b16 v[168:169], v185 offset:0x200
	ds_read_b64_tr_b16 v[170:171], v185 offset:0xa00
	v_mfma_f32_32x32x16_bf16 v[50:65], v[156:159], v[172:175], v[50:65]
	ds_read_b64_tr_b16 v[172:173], v185 offset:0x1200
	ds_read_b64_tr_b16 v[174:175], v185 offset:0x1a00
	v_mfma_f32_32x32x16_bf16 v[50:65], v[160:163], v[176:179], v[50:65]
	ds_read_b64_tr_b16 v[176:177], v185 offset:0x2200
	ds_read_b64_tr_b16 v[178:179], v185 offset:0x2a00
	v_mfma_f32_32x32x16_bf16 v[50:65], v[164:167], v[192:195], v[50:65]
	ds_read_b64_tr_b16 v[192:193], v185 offset:0x3200
	ds_read_b64_tr_b16 v[194:195], v185 offset:0x3a00
	s_waitcnt lgkmcnt(0)
	v_mfma_f32_32x32x16_bf16 v[34:49], v[152:155], v[168:171], v[34:49]
	ds_read_b64_tr_b16 v[168:169], v185 offset:0x400
	ds_read_b64_tr_b16 v[170:171], v185 offset:0xc00
	v_mfma_f32_32x32x16_bf16 v[34:49], v[156:159], v[172:175], v[34:49]
	ds_read_b64_tr_b16 v[172:173], v185 offset:0x1400
	ds_read_b64_tr_b16 v[174:175], v185 offset:0x1c00
	v_mfma_f32_32x32x16_bf16 v[34:49], v[160:163], v[176:179], v[34:49]
	ds_read_b64_tr_b16 v[176:177], v185 offset:0x2400
	ds_read_b64_tr_b16 v[178:179], v185 offset:0x2c00
	v_mfma_f32_32x32x16_bf16 v[34:49], v[164:167], v[192:195], v[34:49]
	ds_read_b64_tr_b16 v[192:193], v185 offset:0x3400
	ds_read_b64_tr_b16 v[194:195], v185 offset:0x3c00
	s_waitcnt lgkmcnt(0)
	v_mfma_f32_32x32x16_bf16 v[18:33], v[152:155], v[168:171], v[18:33]
	ds_read_b64_tr_b16 v[168:169], v185 offset:0x600
	ds_read_b64_tr_b16 v[170:171], v185 offset:0xe00
	v_mfma_f32_32x32x16_bf16 v[18:33], v[156:159], v[172:175], v[18:33]
	ds_read_b64_tr_b16 v[172:173], v185 offset:0x1600
	ds_read_b64_tr_b16 v[174:175], v185 offset:0x1e00
	v_mfma_f32_32x32x16_bf16 v[18:33], v[160:163], v[176:179], v[18:33]
	ds_read_b64_tr_b16 v[176:177], v185 offset:0x2600
	ds_read_b64_tr_b16 v[178:179], v185 offset:0x2e00
	v_mfma_f32_32x32x16_bf16 v[18:33], v[164:167], v[192:195], v[18:33]
	ds_read_b64_tr_b16 v[192:193], v185 offset:0x3600
	ds_read_b64_tr_b16 v[194:195], v185 offset:0x3e00
	s_waitcnt lgkmcnt(0)
	v_mfma_f32_32x32x16_bf16 v[2:17], v[152:155], v[168:171], v[2:17]
	s_lshl_b32 s0, s44, 8
	s_or_b32 s1, s0, 0xff
	s_cmp_le_i32 s1, s6
	v_mfma_f32_32x32x16_bf16 v[2:17], v[156:159], v[172:175], v[2:17]
	v_mfma_f32_32x32x16_bf16 v[2:17], v[160:163], v[176:179], v[2:17]
	v_mfma_f32_32x32x16_bf16 v[2:17], v[164:167], v[192:195], v[2:17]
	s_cbranch_scc1 .LBB0_109
; #define RESC(a) do { if (__any((a) < 1.f)) { if (hi == 0) al_l[r32] = (a); asm volatile("s_waitcnt lgkmcnt(0)" ::: "memory");              \
;                      for (int d_ = 0; d_ < 4; ++d_) for (int r = 0; r < 16; ++r) o[d_][r] *= al_l[crow(r, hi)]; } } while (0)
; #define MASKT(P0_, P1_, t) do { const int kb_ = KBASE(t); if (kb_ + KVBLK - 1 > qlo) mask_tile(P0_, P1_, qm - kb_, (unsigned)W); } while (0)
; __device__ __forceinline__ void mask_tile(f32x16& p0, f32x16& p1, int dq, unsigned W) {
;     const float NEG = -__builtin_inff();
; #pragma unroll
;     for (int r = 0; r < 16; ++r) {
;         const int c = (r & 3) + 8 * (r >> 2);
;         if ((unsigned)(dq - c) >= W) p0[r] = NEG;
;         if ((unsigned)(dq - c - 32) >= W) p1[r] = NEG;
;     }
; }
; __device__ __forceinline__ void moba_block(const BlockRef& cur, const BlockRef& nxt, char* lds, Seam& S) {
;     ...
;     if (even) { MASKT(pB0, pB1, NT - 1); partialSM(pB0, pB1, m_reg, mnB, alB, RSEL(NT - 1)); __syncthreads(); RESC(alB);
	s_or_b32 s0, s0, 0xc0
	v_subrev_u32_e32 v105, s0, v190
	v_cmp_gt_u32_e32 vcc, 2.0, v105
	v_add_u32_e32 v106, 0xbfffffe0, v105
	s_nop 0
	v_cndmask_b32_e32 v66, v220, v66, vcc
	v_cmp_lt_u32_e32 vcc, s33, v106
	v_add_u32_e32 v106, 0xbfffffff, v105
	s_nop 0
	v_cndmask_b32_e32 v82, v220, v82, vcc
	v_cmp_lt_u32_e32 vcc, s33, v106
	v_add_u32_e32 v106, 0xbfffffdf, v105
	s_nop 0
	v_cndmask_b32_e32 v67, v220, v67, vcc
	v_cmp_lt_u32_e32 vcc, s33, v106
	v_add_u32_e32 v106, 0xbffffffe, v105
	s_nop 0
	v_cndmask_b32_e32 v83, v220, v83, vcc
	v_cmp_lt_u32_e32 vcc, s33, v106
	v_add_u32_e32 v106, 0xbfffffde, v105
	s_nop 0
	v_cndmask_b32_e32 v68, v220, v68, vcc
	v_cmp_lt_u32_e32 vcc, s33, v106
	v_add_u32_e32 v106, 0xbffffffd, v105
	s_nop 0
	v_cndmask_b32_e32 v84, v220, v84, vcc
	v_cmp_lt_u32_e32 vcc, s33, v106
	v_add_u32_e32 v106, 0xbfffffdd, v105
	s_nop 0
	v_cndmask_b32_e32 v69, v220, v69, vcc
	v_cmp_lt_u32_e32 vcc, s33, v106
	v_add_u32_e32 v106, 0xbffffff8, v105
	s_nop 0
	v_cndmask_b32_e32 v85, v220, v85, vcc
	v_cmp_lt_u32_e32 vcc, s33, v106
	v_add_u32_e32 v106, 0xbfffffd8, v105
	s_nop 0
	v_cndmask_b32_e32 v70, v220, v70, vcc
	v_cmp_lt_u32_e32 vcc, s33, v106
	v_add_u32_e32 v106, 0xbffffff7, v105
	s_nop 0
	v_cndmask_b32_e32 v86, v220, v86, vcc
	v_cmp_lt_u32_e32 vcc, s33, v106
	v_add_u32_e32 v106, 0xbfffffd7, v105
	s_nop 0
	v_cndmask_b32_e32 v71, v220, v71, vcc
	v_cmp_lt_u32_e32 vcc, s33, v106
	v_add_u32_e32 v106, 0xbffffff6, v105
	s_nop 0
	v_cndmask_b32_e32 v87, v220, v87, vcc
	v_cmp_lt_u32_e32 vcc, s33, v106
	v_add_u32_e32 v106, 0xbfffffd6, v105
	s_nop 0
	v_cndmask_b32_e32 v72, v220, v72, vcc
	v_cmp_lt_u32_e32 vcc, s33, v106
	v_add_u32_e32 v106, 0xbffffff5, v105
	s_nop 0
	v_cndmask_b32_e32 v88, v220, v88, vcc
	v_cmp_lt_u32_e32 vcc, s33, v106
	v_add_u32_e32 v106, 0xbfffffd5, v105
	s_nop 0
	v_cndmask_b32_e32 v73, v220, v73, vcc
	v_cmp_lt_u32_e32 vcc, s33, v106
	v_add_u32_e32 v106, 0xbffffff0, v105
	s_nop 0
	v_cndmask_b32_e32 v89, v220, v89, vcc
	v_cmp_lt_u32_e32 vcc, s33, v106
	v_add_u32_e32 v106, 0xbfffffd0, v105
	s_nop 0
	v_cndmask_b32_e32 v74, v220, v74, vcc
	v_cmp_lt_u32_e32 vcc, s33, v106
	v_add_u32_e32 v106, 0xbfffffef, v105
	s_nop 0
	v_cndmask_b32_e32 v90, v220, v90, vcc
	v_cmp_lt_u32_e32 vcc, s33, v106
	v_add_u32_e32 v106, 0xbfffffcf, v105
	s_nop 0
	v_cndmask_b32_e32 v75, v220, v75, vcc
	v_cmp_lt_u32_e32 vcc, s33, v106
	v_add_u32_e32 v106, 0xbfffffee, v105
	s_nop 0
	v_cndmask_b32_e32 v91, v220, v91, vcc
	v_cmp_lt_u32_e32 vcc, s33, v106
	v_add_u32_e32 v106, 0xbfffffce, v105
	s_nop 0
	v_cndmask_b32_e32 v76, v220, v76, vcc
	v_cmp_lt_u32_e32 vcc, s33, v106
	v_add_u32_e32 v106, 0xbfffffed, v105
	s_nop 0
	v_cndmask_b32_e32 v92, v220, v92, vcc
	v_cmp_lt_u32_e32 vcc, s33, v106
	v_add_u32_e32 v106, 0xbfffffcd, v105
	s_nop 0
	v_cndmask_b32_e32 v77, v220, v77, vcc
	v_cmp_lt_u32_e32 vcc, s33, v106
	v_add_u32_e32 v106, 0xbfffffe8, v105
	s_nop 0
	v_cndmask_b32_e32 v93, v220, v93, vcc
	v_cmp_lt_u32_e32 vcc, s33, v106
	v_add_u32_e32 v106, 0xbfffffc8, v105
	s_nop 0
	v_cndmask_b32_e32 v78, v220, v78, vcc
	v_cmp_lt_u32_e32 vcc, s33, v106
	v_add_u32_e32 v106, 0xbfffffe7, v105
	s_nop 0
	v_cndmask_b32_e32 v94, v220, v94, vcc
	v_cmp_lt_u32_e32 vcc, s33, v106
	v_add_u32_e32 v106, 0xbfffffc7, v105
	s_nop 0
	v_cndmask_b32_e32 v79, v220, v79, vcc
	v_cmp_lt_u32_e32 vcc, s33, v106
	v_add_u32_e32 v106, 0xbfffffe6, v105
	s_nop 0
	v_cndmask_b32_e32 v95, v220, v95, vcc
	v_cmp_lt_u32_e32 vcc, s33, v106
	v_add_u32_e32 v106, 0xbfffffc6, v105
	s_nop 0
	v_cndmask_b32_e32 v80, v220, v80, vcc
	v_cmp_lt_u32_e32 vcc, s33, v106
	v_add_u32_e32 v106, 0xbfffffe5, v105
	v_add_u32_e32 v105, 0xbfffffc5, v105
	v_cndmask_b32_e32 v96, v220, v96, vcc
	v_cmp_lt_u32_e32 vcc, s33, v106
	s_nop 1
	v_cndmask_b32_e32 v81, v220, v81, vcc
	v_cmp_lt_u32_e32 vcc, s33, v105
	s_nop 1
	v_cndmask_b32_e32 v97, v220, v97, vcc
